# diff-attention loop: 2 barrier epochs per tile pair ([QKab SMa PVa]|[SMb PVb]); waves 4-7 run one epoch behind waves 0-3; tile sb+2 V DMA after the mid barrier
# baseline (speedup 1.0000x reference)
; #define WAIT_BAR() do { asm volatile("s_waitcnt vmcnt(0) lgkmcnt(0)" ::: "memory"); __builtin_amdgcn_s_barrier(); asm volatile("" ::: "memory"); } while (0)
; template <bool SWA>
; __device__ __forceinline__ void unit(LAS unsigned char* lds, const bf16_t* PROJ, const bf16_t* KT, const bf16_t* VT, bf16_t* OB, int opitch, int ocol, int b, int head, int qb, float slope2, float m_init, float lam, const float* subg) {
;     ...
;     WAIT_BAR();
;     const int npairs = (nsteps + 1) >> 1;
;     for (int S = 0; S < npairs; ++S) {
.LBB0_882:
	s_waitcnt vmcnt(0) lgkmcnt(0)
	s_barrier
	s_lshl_b32 s0, s16, 1
	s_mov_b32 s77, s76
	s_mov_b32 s22, s76
	s_mov_b32 s38, s76
	s_mov_b32 s39, s76
	s_mov_b32 s40, s76
	s_mov_b32 s41, s76
	s_mov_b32 s48, s76
	s_mov_b32 s49, s76
	s_mov_b32 s50, s76
	s_mov_b32 s51, s76
	s_mov_b32 s8, s76
	s_mov_b32 s3, s76
	s_mov_b32 s43, s76
	s_mov_b32 s97, s76
	s_mov_b32 s24, s76
	s_mov_b32 s26, 0
	s_mov_b32 s1, 5
	s_mov_b32 s25, 0x14000
	s_cmp_eq_u32 s4, 1
	s_cbranch_scc0 .Latt_noextra_b
	s_barrier
.Latt_noextra_b:
	s_branch .LBB0_884

; #define DMA_T(s_) do { DMA_K(s_); DMA_V(s_); } while (0)
; template <bool SWA>
; __device__ __forceinline__ void unit(LAS unsigned char* lds, const bf16_t* PROJ, const bf16_t* KT, const bf16_t* VT, bf16_t* OB, int opitch, int ocol, int b, int head, int qb, float slope2, float m_init, float lam, const float* subg) {
;     ...
;         if (sb + 2 < nsteps) DMA_T(sb + 2);
.Latt_mid:
	s_waitcnt vmcnt(0) lgkmcnt(0)
	s_barrier
	s_mov_b32 m0, s71
	s_nop 0
	global_load_lds_dwordx4 v168, s[100:101]
	s_add_i32 m0, s71, 0x400
	s_nop 0
	global_load_lds_dwordx4 v172, s[100:101]

; #define WAIT_BAR() do { asm volatile("s_waitcnt vmcnt(0) lgkmcnt(0)" ::: "memory"); __builtin_amdgcn_s_barrier(); asm volatile("" ::: "memory"); } while (0)
; template <bool SWA>
; __device__ __forceinline__ void unit(LAS unsigned char* lds, const bf16_t* PROJ, const bf16_t* KT, const bf16_t* VT, bf16_t* OB, int opitch, int ocol, int b, int head, int qb, float slope2, float m_init, float lam, const float* subg) {
;     ...
;         WAIT_BAR();
;     }
;     __syncthreads();
.LBB0_917:
	s_cmp_eq_u32 s4, 0
	s_cbranch_scc0 .Latt_noextra_a
	s_barrier
